# v33 plus: mixer job queue gives each workgroup its own index as first job (no contended atomic at phase start), later jobs = counter + gridDim
# baseline (speedup 1.0000x reference)
; #define LAS __attribute__((address_space(3)))
; __device__ void mixer_phase(const Params& p, int layer, char* smem) {
;   const int natt = 256 + 512 + 512 + (layer == 0 ? 128 : 0);
;   const int njobs = natt + 64;
;   volatile LAS unsigned* slot = (volatile LAS unsigned*)(smem + ST_OFF + 8);
;   unsigned* ctr = p.bar + XCD_BAR_WORDS + 64 * layer;
;   for (;;) {
.LBB0_429:
	s_or_b64 exec, exec, s[0:1]
	v_readlane_b32 s0, v254, 32
	v_readlane_b32 s1, v254, 33
	s_and_b64 s[0:1], s[0:1], exec
	s_movk_i32 s0, 0x5c0
	s_cselect_b32 s27, s0, 0x540
	v_readlane_b32 s0, v255, 1
	v_readlane_b32 s1, v255, 2
	s_lshl_b64 s[0:1], s[0:1], 2
	v_readlane_b32 s2, v253, 38
	s_add_u32 s2, s2, s0
	v_readlane_b32 s0, v253, 39
	s_addc_u32 s3, s0, s1
	v_writelane_b32 v255, s2, 3
	s_lshl_b32 s0, s96, 2
	s_mov_b32 s29, s56
	v_writelane_b32 v255, s3, 4
	v_writelane_b32 v255, s0, 5
	v_readlane_b32 s0, v254, 34
	v_readlane_b32 s1, v254, 35
	s_mov_b32 s2, s96
	s_mov_b32 s3, s1
	v_writelane_b32 v255, s2, 6
	s_lshl_b64 s[0:1], s[2:3], 24
	s_waitcnt lgkmcnt(0)
	v_writelane_b32 v255, s3, 7
	v_readlane_b32 s2, v254, 15
	s_add_u32 s2, s2, s0
	v_readlane_b32 s0, v254, 16
	s_addc_u32 s3, s0, s1
	v_writelane_b32 v255, s2, 8
	s_barrier
	s_nop 0
	v_writelane_b32 v255, s3, 9
	v_writelane_b32 v255, s56, 10
	v_writelane_b32 v255, s27, 11
	v_writelane_b32 v255, s29, 12
	s_mov_b32 s101, 0
	s_branch .LBB0_433

; __device__ void mixer_phase(const Params& p, int layer, char* smem) {
;     ...
;     if (threadIdx.x == 0) *slot = atomicAdd(ctr, 1u);
;     __syncthreads();
;     int job = (int)*slot;
.LBB0_433:
	s_setprio 0
	s_and_saveexec_b64 s[0:1], s[38:39]
	s_cbranch_execz .LBB0_437
	s_cmp_eq_u32 s101, 0
	s_cbranch_scc0 .Ljq_atomic
	s_mov_b32 s101, 1
	s_waitcnt vmcnt(0)
	v_mov_b32_e32 v0, s57
	v_mov_b32_e32 v2, s19
	ds_write_b32 v2, v0
	s_branch .LBB0_437
.Ljq_atomic:
	s_mov_b64 s[4:5], exec
	v_mbcnt_lo_u32_b32 v0, s4, 0
	v_mbcnt_hi_u32_b32 v0, s5, v0
	v_cmp_eq_u32_e32 vcc, 0, v0
	s_and_saveexec_b64 s[2:3], vcc
	s_cbranch_execz .LBB0_436
	s_bcnt1_i32_b64 s4, s[4:5]
	s_waitcnt vmcnt(11)
	v_mov_b32_e32 v2, s4
	v_readlane_b32 s4, v255, 3
	v_readlane_b32 s5, v255, 4
	s_nop 4
	global_atomic_add v2, v1, v2, s[4:5] sc0
.LBB0_436:
	s_or_b64 exec, exec, s[2:3]
	s_waitcnt vmcnt(0)
	v_readfirstlane_b32 s2, v2
	v_mov_b32_e32 v2, s19
	s_nop 1
	s_add_i32 s2, s2, s58
	v_add_u32_e32 v0, s2, v0
	ds_write_b32 v2, v0
